# MLA KV loop: per-tile max tree/vote replaced by exact power-of-two renormalisation of the running row sums checked once per 6 tiles, with an overflow-flagged redo of the unit through the original care
# speedup vs baseline: 1.0453x; 1.0229x over previous
; #define PH(n) if constexpr ((PHASE_MASK >> (n)) & 1)
; __global__ void __launch_bounds__(512, 2) fwd_mega(Args a) {
;     ...
;         PH(11) for (int L = vcu; L < 8 * 8 * 16; L += G) {
;             const int qb = L & 15, bh = L >> 4, b = bh >> 3, h = bh & 7; const size_t row0 = (size_t)b * SEQ + qb * 256;
;             attn_unit<96, 64, 1, true>(lds, Qb + row0 * 768 + h * 96, 768, Kbuf + (size_t)b * SEQ * 768 + h * 96, 768,
;                               Vt + (size_t)(b * 512 + h * 64) * 4096, 4096, SEQ, P + row0 * PW + PC_ZMLA + h * 64, P + row0 * PW + PC_ZMLA + h * 64, PW, wave);
.LBB0_859:
	s_cmpk_gt_i32 s87, 0x3ff
	s_cbranch_scc1 .LBB0_895
	s_add_u32 s3, s6, 0x5000000
	s_addc_u32 s24, s7, 0
	s_add_u32 s25, s6, 0x2000000
	s_addc_u32 s48, s7, 0
	s_add_u32 s49, s10, 0x17000000
	s_addc_u32 s50, s11, 0
	v_add_u32_e32 v0, 64, v187
	s_add_u32 s28, s6, 0x2030000
	v_cmp_lt_i32_e32 vcc, v185, v0
	s_addc_u32 s29, s7, 0
	s_add_u32 s30, s10, 0x17000100
	v_cndmask_b32_e32 v0, v184, v185, vcc
	v_lshlrev_b32_e32 v162, 2, v0
	s_addc_u32 s31, s11, 0
	s_movk_i32 s51, 0x600
	v_mov_b32_e32 v149, 0
	s_mov_b32 s64, 0
	s_mov_b32 s65, 0
	v_mov_b32_e32 v241, 0x10000
	ds_write_b32 v241, v149
	s_movk_i32 s52, 0x300
	s_mov_b32 s53, 0x2aaaaaab
	s_movk_i32 s54, 0xff
	s_movk_i32 s55, 0x100
	s_movk_i32 s56, 0xd0
	s_movk_i32 s57, 0x90
	s_mov_b32 s58, 0xaaaaaaab
	s_mov_b32 s59, 0x41000000
	s_mov_b64 s[34:35], 0x18000
	s_mov_b64 s[36:37], 0x80
	s_movk_i32 s60, 0x2800
	v_mov_b32_e32 v163, 0xc0
	s_mov_b32 s61, s87
	s_branch .LBB0_863

; #define AT_QK_LD0(kb_) do { if constexpr (NEGM) { const LAS unsigned char* kbp_ = Kl + (kb_) * KBUF + r32 * KROWB + hi * 16; AT_KLD2(0); __builtin_amdgcn_sched_barrier(0); } } while (0)
; template <int DQK, int DV, int RH, bool NEGM> ...
;     ...
;             AT_QK_LD0(kb); AT_QK(kb); AT_VLOAD(vs_cur); AT_SOFTMAX(); AT_PV(vs_cur);
;             if (t + 1 < NT) AT_LSTORE(kb ^ 1, vs_next);
;             __syncthreads();
.LBB0_862:
	v_exp_f32_e32 v66, v48
	v_exp_f32_e32 v68, v49
	v_exp_f32_e32 v67, v50
	v_exp_f32_e32 v69, v51
	v_exp_f32_e32 v50, v52
	v_exp_f32_e32 v52, v53
	v_exp_f32_e32 v51, v54
	v_exp_f32_e32 v53, v55
	v_cvt_pk_bf16_f32 v70, v66, v68
	v_cvt_pk_bf16_f32 v71, v67, v69
	v_cvt_pk_bf16_f32 v72, v50, v52
	v_cvt_pk_bf16_f32 v73, v51, v53
	s_mul_i32 s6, s39, 0x2800
	s_mul_hi_u32 s7, s38, 0x2800
	s_waitcnt lgkmcnt(7)
	v_mfma_f32_32x32x16_bf16 v[16:31], v[108:111], v[70:73], v[16:31]
	s_add_i32 s7, s7, s6
	s_mulk_i32 s38, 0x2800
	s_add_u32 s6, s10, s38
	v_exp_f32_e32 v74, v56
	v_exp_f32_e32 v76, v57
	v_exp_f32_e32 v75, v58
	v_exp_f32_e32 v77, v59
	s_waitcnt lgkmcnt(3)
	v_mfma_f32_32x32x16_bf16 v[0:15], v[112:115], v[70:73], v[0:15]
	v_exp_f32_e32 v58, v60
	v_exp_f32_e32 v60, v61
	v_exp_f32_e32 v59, v62
	v_exp_f32_e32 v61, v63
	s_addc_u32 s7, s11, s7
	s_lshl_b32 s8, s46, 1
	s_add_u32 s6, s6, s8
	s_addc_u32 s7, s7, 0
	s_add_u32 s6, s6, 0x3000400
	v_cvt_pk_bf16_f32 v54, v74, v76
	v_cvt_pk_bf16_f32 v55, v75, v77
	v_cvt_pk_bf16_f32 v56, v58, v60
	v_cvt_pk_bf16_f32 v57, v59, v61
	s_addc_u32 s7, s7, 0
	v_lshlrev_b32_e32 v48, 2, v165
	v_mfma_f32_32x32x16_bf16 v[16:31], v[104:107], v[54:57], v[16:31]
	v_mov_b64_e32 v[62:63], s[6:7]
	v_mad_u64_u32 v[62:63], s[6:7], v164, s60, v[62:63]
	v_ashrrev_i32_e32 v49, 31, v48
	v_lshl_add_u64 v[48:49], v[48:49], 1, v[62:63]
	v_exp_f32_e32 v70, v32
	v_exp_f32_e32 v72, v33
	s_waitcnt lgkmcnt(2)
	v_mfma_f32_32x32x16_bf16 v[0:15], v[100:103], v[54:57], v[0:15]
	v_exp_f32_e32 v71, v34
	v_exp_f32_e32 v73, v35
	v_exp_f32_e32 v36, v36
	v_exp_f32_e32 v78, v37
	v_exp_f32_e32 v37, v38
	v_exp_f32_e32 v79, v39
	s_waitcnt lgkmcnt(0)
	s_barrier
	v_mov_b32_e32 v241, 0x10000
	ds_read_b32 v241, v241
	s_waitcnt lgkmcnt(0)
	v_readfirstlane_b32 s67, v241
	s_nop 0
	s_cmp_lg_u32 s67, 0
	s_cbranch_scc1 .Lmla_redo
; #define GAS __attribute__((address_space(1)))
; __device__ __forceinline__ float bf_lo(unsigned w) { return __uint_as_float(w << 16); }
; __device__ __forceinline__ float bf_hi(unsigned w) { return __uint_as_float(w & 0xffff0000u); }
; template <int DQK, int DV, int RH, bool NEGM> ...
;     ...
; #pragma unroll
;     for (int hh = 0; hh < RH; ++hh) {
;         float l = (lacc[hh][0] + lacc[hh][1]) + (lacc[hh][2] + lacc[hh][3]); l += __shfl_xor(l, 32);
;         const float inv = 1.f / l;
;         const size_t ro = (size_t)(wid * 32 * RH + hh * 32 + r32) * zpitch;
; #pragma unroll
;         for (int dt = 0; dt < DV / 32; ++dt)
; #pragma unroll
;             for (int i = 0; i < 4; ++i) {
;                 const int c = dt * 32 + 8 * i + 4 * hi;
;                 const u32x2 zw = *(const GAS u32x2*)(ZI + ro + c);
;                 u32x2 w;
;                 w.x = pk2(o[hh][dt][4 * i + 0] * inv * bf_lo(zw.x), o[hh][dt][4 * i + 1] * inv * bf_hi(zw.x));
;                 w.y = pk2(o[hh][dt][4 * i + 2] * inv * bf_lo(zw.y), o[hh][dt][4 * i + 3] * inv * bf_hi(zw.y));
;                 *(GAS u32x2*)(ZO + ro + c) = w;
;             }
;     }
	global_load_dwordx2 v[62:63], v[48:49], off
	global_load_dwordx2 v[54:55], v[48:49], off offset:16
	global_load_dwordx2 v[56:57], v[48:49], off offset:32
	v_exp_f32_e32 v38, v40
	v_exp_f32_e32 v40, v41
	v_exp_f32_e32 v39, v42
	v_exp_f32_e32 v41, v43
	v_exp_f32_e32 v42, v44
	v_exp_f32_e32 v44, v45
	v_exp_f32_e32 v43, v46
	v_exp_f32_e32 v45, v47
	v_cvt_pk_bf16_f32 v32, v70, v72
	v_cvt_pk_bf16_f32 v33, v71, v73
	v_cvt_pk_bf16_f32 v34, v36, v78
	v_cvt_pk_bf16_f32 v35, v37, v79
	v_pk_add_f32 v[36:37], v[50:51], v[36:37]
	v_pk_add_f32 v[50:51], v[66:67], v[70:71]
	v_mfma_f32_32x32x16_bf16 v[16:31], v[96:99], v[32:35], v[16:31]
	v_add_f32_e64 v52, v52, v78
	v_add_f32_e64 v53, v53, v79
	v_add_f32_e64 v50, v150, v50
	v_add_f32_e64 v51, v151, v51
	global_load_dwordx2 v[46:47], v[48:49], off offset:48
	v_pk_add_f32 v[36:37], v[36:37], v[50:51]
	s_add_i32 s61, s61, s18
	s_cmpk_gt_i32 s61, 0x3ff
	v_mfma_f32_32x32x16_bf16 v[0:15], v[92:95], v[32:35], v[0:15]
	v_cvt_pk_bf16_f32 v34, v42, v44
	v_cvt_pk_bf16_f32 v35, v43, v45
	v_add_f32_e64 v44, v60, v44
	v_add_f32_e64 v45, v61, v45
	v_add_f32_e64 v60, v68, v72
	v_add_f32_e64 v61, v69, v73
	v_cvt_pk_bf16_f32 v32, v38, v40
	v_pk_add_f32 v[60:61], v[64:65], v[60:61]
	v_cvt_pk_bf16_f32 v33, v39, v41
	v_pk_add_f32 v[40:41], v[76:77], v[40:41]
	v_pk_add_f32 v[52:53], v[52:53], v[60:61]
	v_pk_add_f32 v[38:39], v[74:75], v[38:39]
	v_pk_add_f32 v[40:41], v[40:41], v[52:53]
	v_pk_add_f32 v[42:43], v[58:59], v[42:43]
	v_pk_add_f32 v[36:37], v[38:39], v[36:37]
	v_pk_add_f32 v[40:41], v[44:45], v[40:41]
	v_pk_add_f32 v[36:37], v[42:43], v[36:37]
	global_load_dwordx2 v[44:45], v[48:49], off offset:64
	v_pk_add_f32 v[36:37], v[36:37], v[40:41]
	v_mfma_f32_32x32x16_bf16 v[16:31], v[88:91], v[32:35], v[16:31]
	v_add_f32_e32 v38, v36, v37
	ds_bpermute_b32 v39, v162, v38
	global_load_dwordx2 v[36:37], v[48:49], off offset:80
	s_waitcnt lgkmcnt(0)
	v_add_f32_e32 v38, v38, v39
	v_div_scale_f32 v39, s[6:7], v38, v38, 1.0
	v_rcp_f32_e32 v40, v39
	v_mfma_f32_32x32x16_bf16 v[0:15], v[84:87], v[32:35], v[0:15]
	global_load_dwordx2 v[32:33], v[48:49], off offset:96
	v_fma_f32 v34, -v39, v40, 1.0
	v_fmac_f32_e32 v40, v34, v40
	v_div_scale_f32 v34, vcc, 1.0, v38, 1.0
	v_mul_f32_e32 v35, v34, v40
	v_fma_f32 v41, -v39, v35, v34
	v_fmac_f32_e32 v35, v41, v40
	v_fma_f32 v34, -v39, v35, v34
	v_div_fmas_f32 v39, v34, v40, v35
	global_load_dwordx2 v[34:35], v[48:49], off offset:112
	v_div_fixup_f32 v38, v39, v38, 1.0
	v_pk_mul_f32 v[16:17], v[16:17], v[38:39] op_sel_hi:[1,0]
	v_pk_mul_f32 v[18:19], v[18:19], v[38:39] op_sel_hi:[1,0]
	v_pk_mul_f32 v[0:1], v[0:1], v[38:39] op_sel_hi:[1,0]
	v_pk_mul_f32 v[2:3], v[2:3], v[38:39] op_sel_hi:[1,0]
	s_waitcnt vmcnt(7)
	v_lshlrev_b32_e32 v40, 16, v62
	v_and_b32_e32 v41, 0xffff0000, v62
	v_pk_mul_f32 v[16:17], v[16:17], v[40:41]
	v_lshlrev_b32_e32 v40, 16, v63
	v_and_b32_e32 v41, 0xffff0000, v63
	v_pk_mul_f32 v[18:19], v[18:19], v[40:41]
	v_cvt_pk_bf16_f32 v16, v16, v17
	v_cvt_pk_bf16_f32 v17, v18, v19
	global_store_dwordx2 v[48:49], v[16:17], off
	v_pk_mul_f32 v[16:17], v[20:21], v[38:39] op_sel_hi:[1,0]
	s_waitcnt vmcnt(7)
	v_lshlrev_b32_e32 v18, 16, v54
	v_and_b32_e32 v19, 0xffff0000, v54
	v_pk_mul_f32 v[16:17], v[16:17], v[18:19]
	v_pk_mul_f32 v[18:19], v[22:23], v[38:39] op_sel_hi:[1,0]
	v_lshlrev_b32_e32 v20, 16, v55
	v_and_b32_e32 v21, 0xffff0000, v55
	v_pk_mul_f32 v[18:19], v[18:19], v[20:21]
	v_cvt_pk_bf16_f32 v16, v16, v17
	v_cvt_pk_bf16_f32 v17, v18, v19
	global_store_dwordx2 v[48:49], v[16:17], off offset:16
	v_pk_mul_f32 v[16:17], v[24:25], v[38:39] op_sel_hi:[1,0]
	s_waitcnt vmcnt(7)
	v_lshlrev_b32_e32 v18, 16, v56
	v_and_b32_e32 v19, 0xffff0000, v56
	v_pk_mul_f32 v[16:17], v[16:17], v[18:19]
	v_pk_mul_f32 v[18:19], v[26:27], v[38:39] op_sel_hi:[1,0]
	v_lshlrev_b32_e32 v20, 16, v57
	v_and_b32_e32 v21, 0xffff0000, v57
	v_pk_mul_f32 v[18:19], v[18:19], v[20:21]
	v_cvt_pk_bf16_f32 v16, v16, v17
	v_cvt_pk_bf16_f32 v17, v18, v19
	global_store_dwordx2 v[48:49], v[16:17], off offset:32
	v_pk_mul_f32 v[16:17], v[28:29], v[38:39] op_sel_hi:[1,0]
	s_waitcnt vmcnt(7)
	v_lshlrev_b32_e32 v18, 16, v46
	v_and_b32_e32 v19, 0xffff0000, v46
	v_pk_mul_f32 v[16:17], v[16:17], v[18:19]
	v_pk_mul_f32 v[18:19], v[30:31], v[38:39] op_sel_hi:[1,0]
	v_lshlrev_b32_e32 v20, 16, v47
	v_and_b32_e32 v21, 0xffff0000, v47
	v_pk_mul_f32 v[18:19], v[18:19], v[20:21]
	v_cvt_pk_bf16_f32 v16, v16, v17
	v_cvt_pk_bf16_f32 v17, v18, v19
	global_store_dwordx2 v[48:49], v[16:17], off offset:48
	s_waitcnt vmcnt(7)
	v_lshlrev_b32_e32 v16, 16, v44
	v_and_b32_e32 v17, 0xffff0000, v44
	v_pk_mul_f32 v[0:1], v[0:1], v[16:17]
	v_lshlrev_b32_e32 v16, 16, v45
	v_and_b32_e32 v17, 0xffff0000, v45
	v_pk_mul_f32 v[2:3], v[2:3], v[16:17]
	v_cvt_pk_bf16_f32 v0, v0, v1
	v_cvt_pk_bf16_f32 v1, v2, v3
	global_store_dwordx2 v[48:49], v[0:1], off offset:64
	v_pk_mul_f32 v[0:1], v[4:5], v[38:39] op_sel_hi:[1,0]
	s_waitcnt vmcnt(7)
	v_lshlrev_b32_e32 v2, 16, v36
	v_and_b32_e32 v3, 0xffff0000, v36
	v_pk_mul_f32 v[0:1], v[0:1], v[2:3]
	v_pk_mul_f32 v[2:3], v[6:7], v[38:39] op_sel_hi:[1,0]
	v_lshlrev_b32_e32 v4, 16, v37
	v_and_b32_e32 v5, 0xffff0000, v37
	v_pk_mul_f32 v[2:3], v[2:3], v[4:5]
	v_cvt_pk_bf16_f32 v0, v0, v1
	v_cvt_pk_bf16_f32 v1, v2, v3
	global_store_dwordx2 v[48:49], v[0:1], off offset:80
	v_pk_mul_f32 v[0:1], v[8:9], v[38:39] op_sel_hi:[1,0]
	s_waitcnt vmcnt(7)
	v_lshlrev_b32_e32 v2, 16, v32
	v_and_b32_e32 v3, 0xffff0000, v32
	v_pk_mul_f32 v[0:1], v[0:1], v[2:3]
	v_pk_mul_f32 v[2:3], v[10:11], v[38:39] op_sel_hi:[1,0]
	v_lshlrev_b32_e32 v4, 16, v33
	v_and_b32_e32 v5, 0xffff0000, v33
	v_pk_mul_f32 v[2:3], v[2:3], v[4:5]
	v_cvt_pk_bf16_f32 v0, v0, v1
	v_cvt_pk_bf16_f32 v1, v2, v3
	global_store_dwordx2 v[48:49], v[0:1], off offset:96
	v_pk_mul_f32 v[0:1], v[12:13], v[38:39] op_sel_hi:[1,0]
	s_waitcnt vmcnt(7)
	v_lshlrev_b32_e32 v2, 16, v34
	v_and_b32_e32 v3, 0xffff0000, v34
	v_pk_mul_f32 v[0:1], v[0:1], v[2:3]
	v_pk_mul_f32 v[2:3], v[14:15], v[38:39] op_sel_hi:[1,0]
	v_lshlrev_b32_e32 v4, 16, v35
	v_and_b32_e32 v5, 0xffff0000, v35
	v_pk_mul_f32 v[2:3], v[2:3], v[4:5]
	v_cvt_pk_bf16_f32 v0, v0, v1
	v_cvt_pk_bf16_f32 v1, v2, v3
	global_store_dwordx2 v[48:49], v[0:1], off offset:112
	s_mov_b32 s65, 0
	s_barrier
	s_cbranch_scc1 .LBB0_895

; #define AT_QK_LD0(kb_) do { if constexpr (NEGM) { const LAS unsigned char* kbp_ = Kl + (kb_) * KBUF + r32 * KROWB + hi * 16; AT_KLD2(0); __builtin_amdgcn_sched_barrier(0); } } while (0)
; template <int DQK, int DV, int RH, bool NEGM> ...
;     ...
;         for (int t = 0; t < NT; ++t) {
;             const int kb = t & 1;
;             if (t + 1 < NT) AT_GLOAD(t + 1);
;             f32x16 p[RH][2];
;             AT_QK_LD0(kb); AT_QK(kb); AT_VLOAD(vs_cur); AT_SOFTMAX(); AT_PV(vs_cur);
;             if (t + 1 < NT) AT_LSTORE(kb ^ 1, vs_next);
;             __syncthreads();
;             vs_prev = vs_cur; vs_cur = vs_next; vs_next = (vs_next == 2) ? 0 : vs_next + 1;
.LBB0_881:
	s_or_b64 exec, exec, s[42:43]
	v_pk_add_f32 v[48:49], v[48:49], v[54:55]
	v_pk_add_f32 v[64:65], v[128:129], v[64:65]
	v_pk_add_f32 v[48:49], v[58:59], v[48:49] op_sel_hi:[0,1]
	v_pk_add_f32 v[52:53], v[52:53], v[56:57]
	v_pk_add_f32 v[48:49], v[64:65], v[48:49]
	v_pk_add_f32 v[70:71], v[118:119], v[70:71]
	v_pk_add_f32 v[48:49], v[52:53], v[48:49]
	v_add_u32_e32 v54, v136, v135
	v_pk_add_f32 v[150:151], v[70:71], v[48:49]
	v_add_u32_e32 v48, 0x8c00, v166
	s_waitcnt vmcnt(0)
	ds_write2_b64 v48, v[74:75], v[76:77] offset1:2
	v_mul_lo_u32 v48, v54, 12
	v_sub_u32_e32 v52, v133, v48
	s_lshr_b32 s21, s61, 4
	v_lshlrev_b32_e32 v48, 3, v52
	v_lshlrev_b32_e32 v175, 4, v52
	v_mov_b64_e32 v[52:53], s[40:41]
	s_and_b32 s42, s21, 7
	v_mul_lo_u32 v174, v54, s56
	v_mad_i64_i32 v[54:55], s[40:41], v54, s51, v[52:53]
	v_pk_add_f32 v[50:51], v[50:51], v[62:63]
	v_ashrrev_i32_e32 v49, 31, v48
	v_mad_u64_u32 v[54:55], s[40:41], s42, v163, v[54:55]
	v_pk_add_f32 v[66:67], v[130:131], v[66:67]
	v_pk_add_f32 v[50:51], v[58:59], v[50:51] op_sel_hi:[0,1]
	v_lshl_add_u64 v[48:49], v[48:49], 1, v[54:55]
	v_pk_add_f32 v[56:57], v[116:117], v[68:69]
	v_pk_add_f32 v[50:51], v[66:67], v[50:51]
	v_mov_b32_e32 v154, v48
	v_mad_i64_i32 v[48:49], s[40:41], v59, s51, v[52:53]
	v_pk_add_f32 v[60:61], v[60:61], v[72:73]
	v_pk_add_f32 v[50:51], v[56:57], v[50:51]
	s_lshl_b32 s43, s42, 6
	v_mad_u64_u32 v[48:49], s[40:41], s42, v163, v[48:49]
	v_pk_add_f32 v[152:153], v[60:61], v[50:51]
	v_lshlrev_b32_e32 v50, 3, v112
	s_add_i32 s40, s47, s43
	v_ashrrev_i32_e32 v51, 31, v50
	s_ashr_i32 s41, s40, 31
	v_lshl_add_u64 v[48:49], v[50:51], 1, v[48:49]
	s_lshl_b64 s[40:41], s[40:41], 13
	v_and_b32_e32 v50, 7, v132
	v_mov_b32_e32 v156, v48
	v_lshl_add_u64 v[48:49], v[78:79], 0, s[40:41]
	v_lshlrev_b32_e32 v148, 4, v50
	v_lshl_add_u64 v[48:49], v[48:49], 0, v[148:149]
	v_mul_u32_u24_e32 v173, 0x90, v134
	s_mov_b32 s21, 1
	v_mov_b32_e32 v158, v48
	s_mov_b32 s42, 2
	s_mov_b32 s43, 1
	s_waitcnt lgkmcnt(0)
	s_barrier
	s_mov_b64 s[98:99], s[28:29]
	s_mov_b64 s[100:101], s[30:31]
	v_add_u32_e32 v244, v174, v175
	v_add_u32_e32 v245, v171, v172
	s_cmp_eq_u32 s65, 0
	s_cbranch_scc0 .Lmlac_loop
.Lmla_loop:
	v_max3_f32 v148, v150, v151, v152
	v_max_f32_e32 v148, v148, v153
	v_cmp_nge_f32_e32 vcc, 0x49800000, v148
	s_cbranch_vccnz .Lmla_renorm
.Lmla_renorm_back:
	ds_read_b128 v[48:51], v169 offset:13312
	ds_read_b128 v[52:55], v169 offset:13344
	ds_read_b128 v[116:119], v169 offset:19968
	ds_read_b128 v[120:123], v169 offset:20000
	global_load_dwordx4 v[104:107], v154, s[98:99]
	s_mov_b64 exec, s[8:9]
	global_load_dwordx4 v[108:111], v156, s[98:99]
	s_mov_b64 exec, -1
	global_load_dwordx4 v[112:115], v158, s[100:101]
	s_add_u32 s98, s98, 0x18000
	s_addc_u32 s99, s99, 0
	s_add_u32 s100, s100, 0x80
	s_addc_u32 s101, s101, 0
	s_waitcnt lgkmcnt(3)
	v_mfma_f32_32x32x16_bf16 v[64:79], v[48:51], v[100:103], v[32:47]
	ds_read_b128 v[124:127], v169 offset:13376
	ds_read_b128 v[128:131], v169 offset:13408
	ds_read_b128 v[132:135], v169 offset:20032
	ds_read_b128 v[136:139], v169 offset:20064
	s_waitcnt lgkmcnt(4)
	v_mfma_f32_32x32x16_bf16 v[64:79], v[52:55], v[96:99], v[64:79]
	v_mfma_f32_32x32x16_bf16 v[48:63], v[116:119], v[100:103], v[32:47]
	v_mfma_f32_32x32x16_bf16 v[48:63], v[120:123], v[96:99], v[48:63]
	s_waitcnt lgkmcnt(1)
	v_mfma_f32_32x32x16_bf16 v[64:79], v[124:127], v[92:95], v[64:79]
	v_mfma_f32_32x32x16_bf16 v[48:63], v[132:135], v[92:95], v[48:63]
	v_mfma_f32_32x32x16_bf16 v[64:79], v[128:131], v[88:91], v[64:79]
	ds_read_b128 v[116:119], v169 offset:13440
	ds_read_b128 v[120:123], v169 offset:13472
	ds_read_b128 v[128:131], v169 offset:20096
	ds_read_b128 v[176:179], v169 offset:20128
	s_waitcnt lgkmcnt(3)
	v_mfma_f32_32x32x16_bf16 v[48:63], v[136:139], v[88:91], v[48:63]
	v_mfma_f32_32x32x16_bf16 v[64:79], v[116:119], v[84:87], v[64:79]
	ds_read_b128 v[136:139], v170 offset:35840
	ds_read_b128 v[124:127], v170 offset:35872
	s_waitcnt lgkmcnt(3)
	v_mfma_f32_32x32x16_bf16 v[48:63], v[128:131], v[84:87], v[48:63]
	v_mfma_f32_32x32x16_bf16 v[64:79], v[120:123], v[80:83], v[64:79]
	ds_read_b128 v[132:135], v170 offset:35904
	ds_read_b128 v[120:123], v170 offset:35936
	ds_read_b128 v[144:147], v170 offset:40448
	ds_read_b128 v[140:143], v170 offset:40480
	ds_read_b128 v[128:131], v170 offset:40512
	ds_read_b128 v[116:119], v170 offset:40544
	s_waitcnt lgkmcnt(8)
	v_mfma_f32_32x32x16_bf16 v[48:63], v[176:179], v[80:83], v[48:63]
	s_add_i32 s43, s43, 1
	s_nop 3
	v_exp_f32_e32 v160, v64
	v_exp_f32_e32 v161, v65
	v_exp_f32_e32 v64, v66
	v_exp_f32_e32 v65, v67
	v_exp_f32_e32 v68, v68
	v_exp_f32_e32 v69, v69
	v_exp_f32_e32 v66, v70
	v_exp_f32_e32 v67, v71
	v_cvt_pk_bf16_f32 v176, v160, v161
	v_cvt_pk_bf16_f32 v177, v64, v65
	v_cvt_pk_bf16_f32 v178, v68, v69
	v_cvt_pk_bf16_f32 v179, v66, v67
	v_exp_f32_e32 v70, v74
	v_exp_f32_e32 v71, v75
	s_waitcnt lgkmcnt(0)
	v_mfma_f32_32x32x16_bf16 v[16:31], v[136:139], v[176:179], v[16:31]
	v_exp_f32_e32 v136, v72
	v_exp_f32_e32 v137, v73
	v_exp_f32_e32 v74, v76
	v_exp_f32_e32 v75, v77
	v_exp_f32_e32 v72, v78
	v_exp_f32_e32 v73, v79
	v_exp_f32_e32 v76, v48
	v_mfma_f32_32x32x16_bf16 v[0:15], v[144:147], v[176:179], v[0:15]
	v_cvt_pk_bf16_f32 v144, v136, v137
	v_cvt_pk_bf16_f32 v145, v70, v71
	v_cvt_pk_bf16_f32 v146, v74, v75
	v_cvt_pk_bf16_f32 v147, v72, v73
	v_exp_f32_e32 v77, v49
	v_exp_f32_e32 v48, v50
	v_exp_f32_e32 v49, v51
	v_mfma_f32_32x32x16_bf16 v[16:31], v[124:127], v[144:147], v[16:31]
	v_exp_f32_e32 v52, v52
	v_exp_f32_e32 v53, v53
	v_exp_f32_e32 v50, v54
	v_exp_f32_e32 v51, v55
	v_cvt_pk_bf16_f32 v124, v76, v77
	v_cvt_pk_bf16_f32 v125, v48, v49
	v_cvt_pk_bf16_f32 v126, v52, v53
	v_mfma_f32_32x32x16_bf16 v[0:15], v[140:143], v[144:147], v[0:15]
	v_cvt_pk_bf16_f32 v127, v50, v51
	v_exp_f32_e32 v78, v56
	v_exp_f32_e32 v79, v57
	v_exp_f32_e32 v54, v58
	v_exp_f32_e32 v55, v59
	v_exp_f32_e32 v58, v60
	v_exp_f32_e32 v59, v61
	v_mfma_f32_32x32x16_bf16 v[16:31], v[132:135], v[124:127], v[16:31]
	v_exp_f32_e32 v56, v62
	v_exp_f32_e32 v57, v63
	v_cvt_pk_bf16_f32 v60, v78, v79
	v_cvt_pk_bf16_f32 v61, v54, v55
	v_cvt_pk_bf16_f32 v62, v58, v59
	v_cvt_pk_bf16_f32 v63, v56, v57
	v_mfma_f32_32x32x16_bf16 v[0:15], v[128:131], v[124:127], v[0:15]
	v_mfma_f32_32x32x16_bf16 v[16:31], v[120:123], v[60:63], v[16:31]
	v_mfma_f32_32x32x16_bf16 v[0:15], v[116:119], v[60:63], v[0:15]
	s_waitcnt vmcnt(1)
	ds_write_b128 v244, v[104:107]
	s_mov_b64 exec, s[8:9]
	ds_write_b128 v245, v[108:111]
	s_mov_b64 exec, -1
	s_waitcnt vmcnt(0)
	ds_write2_b64 v247, v[112:113], v[114:115] offset1:2
	v_pk_add_f32 v[48:49], v[64:65], v[48:49]
	v_pk_add_f32 v[60:61], v[160:161], v[76:77]
	v_pk_add_f32 v[48:49], v[152:153], v[48:49]
	v_pk_add_f32 v[50:51], v[66:67], v[50:51]
	v_pk_add_f32 v[60:61], v[150:151], v[60:61]
	v_pk_add_f32 v[52:53], v[68:69], v[52:53]
	v_pk_add_f32 v[48:49], v[50:51], v[48:49]
	v_pk_add_f32 v[50:51], v[70:71], v[54:55]
	v_pk_add_f32 v[52:53], v[52:53], v[60:61]
	v_pk_add_f32 v[60:61], v[136:137], v[78:79]
	v_pk_add_f32 v[48:49], v[50:51], v[48:49]
	v_pk_add_f32 v[50:51], v[72:73], v[56:57]
	v_pk_add_f32 v[52:53], v[60:61], v[52:53]
	v_pk_add_f32 v[58:59], v[74:75], v[58:59]
	v_pk_add_f32 v[152:153], v[50:51], v[48:49]
	v_pk_add_f32 v[150:151], v[58:59], v[52:53]
	s_waitcnt lgkmcnt(0)
	s_barrier
	ds_read_b128 v[48:51], v169
	ds_read_b128 v[52:55], v169 offset:32
	ds_read_b128 v[116:119], v169 offset:6656
	ds_read_b128 v[120:123], v169 offset:6688
	global_load_dwordx4 v[104:107], v154, s[98:99]
	s_mov_b64 exec, s[8:9]
	global_load_dwordx4 v[108:111], v156, s[98:99]
	s_mov_b64 exec, -1
	global_load_dwordx4 v[112:115], v158, s[100:101]
	s_add_u32 s98, s98, 0x18000
	s_addc_u32 s99, s99, 0
	s_add_u32 s100, s100, 0x80
	s_addc_u32 s101, s101, 0
	s_waitcnt lgkmcnt(3)
	v_mfma_f32_32x32x16_bf16 v[64:79], v[48:51], v[100:103], v[32:47]
	ds_read_b128 v[124:127], v169 offset:64
	ds_read_b128 v[128:131], v169 offset:96
	ds_read_b128 v[132:135], v169 offset:6720
	ds_read_b128 v[136:139], v169 offset:6752
	s_waitcnt lgkmcnt(4)
	v_mfma_f32_32x32x16_bf16 v[64:79], v[52:55], v[96:99], v[64:79]
	v_mfma_f32_32x32x16_bf16 v[48:63], v[116:119], v[100:103], v[32:47]
	v_mfma_f32_32x32x16_bf16 v[48:63], v[120:123], v[96:99], v[48:63]
	s_waitcnt lgkmcnt(1)
	v_mfma_f32_32x32x16_bf16 v[64:79], v[124:127], v[92:95], v[64:79]
	v_mfma_f32_32x32x16_bf16 v[48:63], v[132:135], v[92:95], v[48:63]
	v_mfma_f32_32x32x16_bf16 v[64:79], v[128:131], v[88:91], v[64:79]
	ds_read_b128 v[116:119], v169 offset:128
	ds_read_b128 v[120:123], v169 offset:160
	ds_read_b128 v[128:131], v169 offset:6784
	ds_read_b128 v[176:179], v169 offset:6816
	s_waitcnt lgkmcnt(3)
	v_mfma_f32_32x32x16_bf16 v[48:63], v[136:139], v[88:91], v[48:63]
	v_mfma_f32_32x32x16_bf16 v[64:79], v[116:119], v[84:87], v[64:79]
	ds_read_b128 v[136:139], v170 offset:45056
	ds_read_b128 v[124:127], v170 offset:45088
	s_waitcnt lgkmcnt(3)
	v_mfma_f32_32x32x16_bf16 v[48:63], v[128:131], v[84:87], v[48:63]
	v_mfma_f32_32x32x16_bf16 v[64:79], v[120:123], v[80:83], v[64:79]
	ds_read_b128 v[132:135], v170 offset:45120
	ds_read_b128 v[120:123], v170 offset:45152
	ds_read_b128 v[144:147], v170 offset:49664
	ds_read_b128 v[140:143], v170 offset:49696
	ds_read_b128 v[128:131], v170 offset:49728
	ds_read_b128 v[116:119], v170 offset:49760
	s_waitcnt lgkmcnt(8)
	v_mfma_f32_32x32x16_bf16 v[48:63], v[176:179], v[80:83], v[48:63]
	s_add_i32 s43, s43, 1
	s_nop 3
	v_exp_f32_e32 v160, v64
	v_exp_f32_e32 v161, v65
	v_exp_f32_e32 v64, v66
	v_exp_f32_e32 v65, v67
	v_exp_f32_e32 v68, v68
	v_exp_f32_e32 v69, v69
	v_exp_f32_e32 v66, v70
	v_exp_f32_e32 v67, v71
	v_cvt_pk_bf16_f32 v176, v160, v161
	v_cvt_pk_bf16_f32 v177, v64, v65
	v_cvt_pk_bf16_f32 v178, v68, v69
	v_cvt_pk_bf16_f32 v179, v66, v67
	v_exp_f32_e32 v70, v74
	v_exp_f32_e32 v71, v75
	s_waitcnt lgkmcnt(0)
	v_mfma_f32_32x32x16_bf16 v[16:31], v[136:139], v[176:179], v[16:31]
	v_exp_f32_e32 v136, v72
	v_exp_f32_e32 v137, v73
	v_exp_f32_e32 v74, v76
	v_exp_f32_e32 v75, v77
	v_exp_f32_e32 v72, v78
	v_exp_f32_e32 v73, v79
	v_exp_f32_e32 v76, v48
	v_mfma_f32_32x32x16_bf16 v[0:15], v[144:147], v[176:179], v[0:15]
	v_cvt_pk_bf16_f32 v144, v136, v137
	v_cvt_pk_bf16_f32 v145, v70, v71
	v_cvt_pk_bf16_f32 v146, v74, v75
	v_cvt_pk_bf16_f32 v147, v72, v73
	v_exp_f32_e32 v77, v49
	v_exp_f32_e32 v48, v50
	v_exp_f32_e32 v49, v51
	v_mfma_f32_32x32x16_bf16 v[16:31], v[124:127], v[144:147], v[16:31]
	v_exp_f32_e32 v52, v52
	v_exp_f32_e32 v53, v53
	v_exp_f32_e32 v50, v54
	v_exp_f32_e32 v51, v55
	v_cvt_pk_bf16_f32 v124, v76, v77
	v_cvt_pk_bf16_f32 v125, v48, v49
	v_cvt_pk_bf16_f32 v126, v52, v53
	v_mfma_f32_32x32x16_bf16 v[0:15], v[140:143], v[144:147], v[0:15]
	v_cvt_pk_bf16_f32 v127, v50, v51
	v_exp_f32_e32 v78, v56
	v_exp_f32_e32 v79, v57
	v_exp_f32_e32 v54, v58
	v_exp_f32_e32 v55, v59
	v_exp_f32_e32 v58, v60
	v_exp_f32_e32 v59, v61
	v_mfma_f32_32x32x16_bf16 v[16:31], v[132:135], v[124:127], v[16:31]
	v_exp_f32_e32 v56, v62
	v_exp_f32_e32 v57, v63
	v_cvt_pk_bf16_f32 v60, v78, v79
	v_cvt_pk_bf16_f32 v61, v54, v55
	v_cvt_pk_bf16_f32 v62, v58, v59
	v_cvt_pk_bf16_f32 v63, v56, v57
	v_mfma_f32_32x32x16_bf16 v[0:15], v[128:131], v[124:127], v[0:15]
	v_mfma_f32_32x32x16_bf16 v[16:31], v[120:123], v[60:63], v[16:31]
	v_mfma_f32_32x32x16_bf16 v[0:15], v[116:119], v[60:63], v[0:15]
	s_waitcnt vmcnt(1)
	ds_write_b128 v244, v[104:107] offset:13312
	s_mov_b64 exec, s[8:9]
	ds_write_b128 v245, v[108:111] offset:13312
	s_mov_b64 exec, -1
	s_waitcnt vmcnt(0)
	ds_write2_b64 v243, v[112:113], v[114:115] offset1:2
	v_pk_add_f32 v[48:49], v[64:65], v[48:49]
	v_pk_add_f32 v[60:61], v[160:161], v[76:77]
	v_pk_add_f32 v[48:49], v[152:153], v[48:49]
	v_pk_add_f32 v[50:51], v[66:67], v[50:51]
	v_pk_add_f32 v[60:61], v[150:151], v[60:61]
	v_pk_add_f32 v[52:53], v[68:69], v[52:53]
	v_pk_add_f32 v[48:49], v[50:51], v[48:49]
	v_pk_add_f32 v[50:51], v[70:71], v[54:55]
	v_pk_add_f32 v[52:53], v[52:53], v[60:61]
	v_pk_add_f32 v[60:61], v[136:137], v[78:79]
	v_pk_add_f32 v[48:49], v[50:51], v[48:49]
	v_pk_add_f32 v[50:51], v[72:73], v[56:57]
	v_pk_add_f32 v[52:53], v[60:61], v[52:53]
	v_pk_add_f32 v[58:59], v[74:75], v[58:59]
	v_pk_add_f32 v[152:153], v[50:51], v[48:49]
	v_pk_add_f32 v[150:151], v[58:59], v[52:53]
	s_cmp_lg_u32 s43, 63
	s_waitcnt lgkmcnt(0)
	s_barrier
	s_cbranch_scc0 .Lmla_exit
	ds_read_b128 v[48:51], v169 offset:13312
	ds_read_b128 v[52:55], v169 offset:13344
	ds_read_b128 v[116:119], v169 offset:19968
	ds_read_b128 v[120:123], v169 offset:20000
	global_load_dwordx4 v[104:107], v154, s[98:99]
	s_mov_b64 exec, s[8:9]
	global_load_dwordx4 v[108:111], v156, s[98:99]
	s_mov_b64 exec, -1
	global_load_dwordx4 v[112:115], v158, s[100:101]
	s_add_u32 s98, s98, 0x18000
	s_addc_u32 s99, s99, 0
	s_add_u32 s100, s100, 0x80
	s_addc_u32 s101, s101, 0
	s_waitcnt lgkmcnt(3)
	v_mfma_f32_32x32x16_bf16 v[64:79], v[48:51], v[100:103], v[32:47]
	ds_read_b128 v[124:127], v169 offset:13376
	ds_read_b128 v[128:131], v169 offset:13408
	ds_read_b128 v[132:135], v169 offset:20032
	ds_read_b128 v[136:139], v169 offset:20064
	s_waitcnt lgkmcnt(4)
	v_mfma_f32_32x32x16_bf16 v[64:79], v[52:55], v[96:99], v[64:79]
	v_mfma_f32_32x32x16_bf16 v[48:63], v[116:119], v[100:103], v[32:47]
	v_mfma_f32_32x32x16_bf16 v[48:63], v[120:123], v[96:99], v[48:63]
	s_waitcnt lgkmcnt(1)
	v_mfma_f32_32x32x16_bf16 v[64:79], v[124:127], v[92:95], v[64:79]
	v_mfma_f32_32x32x16_bf16 v[48:63], v[132:135], v[92:95], v[48:63]
	v_mfma_f32_32x32x16_bf16 v[64:79], v[128:131], v[88:91], v[64:79]
	ds_read_b128 v[116:119], v169 offset:13440
	ds_read_b128 v[120:123], v169 offset:13472
	ds_read_b128 v[128:131], v169 offset:20096
	ds_read_b128 v[176:179], v169 offset:20128
	s_waitcnt lgkmcnt(3)
	v_mfma_f32_32x32x16_bf16 v[48:63], v[136:139], v[88:91], v[48:63]
	v_mfma_f32_32x32x16_bf16 v[64:79], v[116:119], v[84:87], v[64:79]
	ds_read_b128 v[136:139], v170 offset:26624
	ds_read_b128 v[124:127], v170 offset:26656
	s_waitcnt lgkmcnt(3)
	v_mfma_f32_32x32x16_bf16 v[48:63], v[128:131], v[84:87], v[48:63]
	v_mfma_f32_32x32x16_bf16 v[64:79], v[120:123], v[80:83], v[64:79]
	ds_read_b128 v[132:135], v170 offset:26688
	ds_read_b128 v[120:123], v170 offset:26720
	ds_read_b128 v[144:147], v170 offset:31232
	ds_read_b128 v[140:143], v170 offset:31264
	ds_read_b128 v[128:131], v170 offset:31296
	ds_read_b128 v[116:119], v170 offset:31328
	s_waitcnt lgkmcnt(8)
	v_mfma_f32_32x32x16_bf16 v[48:63], v[176:179], v[80:83], v[48:63]
	s_add_i32 s43, s43, 1
	s_nop 3
	v_exp_f32_e32 v160, v64
	v_exp_f32_e32 v161, v65
	v_exp_f32_e32 v64, v66
	v_exp_f32_e32 v65, v67
	v_exp_f32_e32 v68, v68
	v_exp_f32_e32 v69, v69
	v_exp_f32_e32 v66, v70
	v_exp_f32_e32 v67, v71
	v_cvt_pk_bf16_f32 v176, v160, v161
	v_cvt_pk_bf16_f32 v177, v64, v65
	v_cvt_pk_bf16_f32 v178, v68, v69
	v_cvt_pk_bf16_f32 v179, v66, v67
	v_exp_f32_e32 v70, v74
	v_exp_f32_e32 v71, v75
	s_waitcnt lgkmcnt(0)
	v_mfma_f32_32x32x16_bf16 v[16:31], v[136:139], v[176:179], v[16:31]
	v_exp_f32_e32 v136, v72
	v_exp_f32_e32 v137, v73
	v_exp_f32_e32 v74, v76
	v_exp_f32_e32 v75, v77
	v_exp_f32_e32 v72, v78
	v_exp_f32_e32 v73, v79
	v_exp_f32_e32 v76, v48
	v_mfma_f32_32x32x16_bf16 v[0:15], v[144:147], v[176:179], v[0:15]
	v_cvt_pk_bf16_f32 v144, v136, v137
	v_cvt_pk_bf16_f32 v145, v70, v71
	v_cvt_pk_bf16_f32 v146, v74, v75
	v_cvt_pk_bf16_f32 v147, v72, v73
	v_exp_f32_e32 v77, v49
	v_exp_f32_e32 v48, v50
	v_exp_f32_e32 v49, v51
	v_mfma_f32_32x32x16_bf16 v[16:31], v[124:127], v[144:147], v[16:31]
	v_exp_f32_e32 v52, v52
	v_exp_f32_e32 v53, v53
	v_exp_f32_e32 v50, v54
	v_exp_f32_e32 v51, v55
	v_cvt_pk_bf16_f32 v124, v76, v77
	v_cvt_pk_bf16_f32 v125, v48, v49
	v_cvt_pk_bf16_f32 v126, v52, v53
	v_mfma_f32_32x32x16_bf16 v[0:15], v[140:143], v[144:147], v[0:15]
	v_cvt_pk_bf16_f32 v127, v50, v51
	v_exp_f32_e32 v78, v56
	v_exp_f32_e32 v79, v57
	v_exp_f32_e32 v54, v58
	v_exp_f32_e32 v55, v59
	v_exp_f32_e32 v58, v60
	v_exp_f32_e32 v59, v61
	v_mfma_f32_32x32x16_bf16 v[16:31], v[132:135], v[124:127], v[16:31]
	v_exp_f32_e32 v56, v62
	v_exp_f32_e32 v57, v63
	v_cvt_pk_bf16_f32 v60, v78, v79
	v_cvt_pk_bf16_f32 v61, v54, v55
	v_cvt_pk_bf16_f32 v62, v58, v59
	v_cvt_pk_bf16_f32 v63, v56, v57
	v_mfma_f32_32x32x16_bf16 v[0:15], v[128:131], v[124:127], v[0:15]
	v_mfma_f32_32x32x16_bf16 v[16:31], v[120:123], v[60:63], v[16:31]
	v_mfma_f32_32x32x16_bf16 v[0:15], v[116:119], v[60:63], v[0:15]
	s_waitcnt vmcnt(1)
	ds_write_b128 v244, v[104:107]
	s_mov_b64 exec, s[8:9]
	ds_write_b128 v245, v[108:111]
	s_mov_b64 exec, -1
	s_waitcnt vmcnt(0)
	ds_write2_b64 v246, v[112:113], v[114:115] offset1:2
	v_pk_add_f32 v[48:49], v[64:65], v[48:49]
	v_pk_add_f32 v[60:61], v[160:161], v[76:77]
	v_pk_add_f32 v[48:49], v[152:153], v[48:49]
	v_pk_add_f32 v[50:51], v[66:67], v[50:51]
	v_pk_add_f32 v[60:61], v[150:151], v[60:61]
	v_pk_add_f32 v[52:53], v[68:69], v[52:53]
	v_pk_add_f32 v[48:49], v[50:51], v[48:49]
	v_pk_add_f32 v[50:51], v[70:71], v[54:55]
	v_pk_add_f32 v[52:53], v[52:53], v[60:61]
	v_pk_add_f32 v[60:61], v[136:137], v[78:79]
	v_pk_add_f32 v[48:49], v[50:51], v[48:49]
	v_pk_add_f32 v[50:51], v[72:73], v[56:57]
	v_pk_add_f32 v[52:53], v[60:61], v[52:53]
	v_pk_add_f32 v[58:59], v[74:75], v[58:59]
	v_pk_add_f32 v[152:153], v[50:51], v[48:49]
	v_pk_add_f32 v[150:151], v[58:59], v[52:53]
	s_waitcnt lgkmcnt(0)
	s_barrier
	ds_read_b128 v[48:51], v169
	ds_read_b128 v[52:55], v169 offset:32
	ds_read_b128 v[116:119], v169 offset:6656
	ds_read_b128 v[120:123], v169 offset:6688
	global_load_dwordx4 v[104:107], v154, s[98:99]
	s_mov_b64 exec, s[8:9]
	global_load_dwordx4 v[108:111], v156, s[98:99]
	s_mov_b64 exec, -1
	global_load_dwordx4 v[112:115], v158, s[100:101]
	s_add_u32 s98, s98, 0x18000
	s_addc_u32 s99, s99, 0
	s_add_u32 s100, s100, 0x80
	s_addc_u32 s101, s101, 0
	s_waitcnt lgkmcnt(3)
	v_mfma_f32_32x32x16_bf16 v[64:79], v[48:51], v[100:103], v[32:47]
	ds_read_b128 v[124:127], v169 offset:64
	ds_read_b128 v[128:131], v169 offset:96
	ds_read_b128 v[132:135], v169 offset:6720
	ds_read_b128 v[136:139], v169 offset:6752
	s_waitcnt lgkmcnt(4)
	v_mfma_f32_32x32x16_bf16 v[64:79], v[52:55], v[96:99], v[64:79]
	v_mfma_f32_32x32x16_bf16 v[48:63], v[116:119], v[100:103], v[32:47]
	v_mfma_f32_32x32x16_bf16 v[48:63], v[120:123], v[96:99], v[48:63]
	s_waitcnt lgkmcnt(1)
	v_mfma_f32_32x32x16_bf16 v[64:79], v[124:127], v[92:95], v[64:79]
	v_mfma_f32_32x32x16_bf16 v[48:63], v[132:135], v[92:95], v[48:63]
	v_mfma_f32_32x32x16_bf16 v[64:79], v[128:131], v[88:91], v[64:79]
	ds_read_b128 v[116:119], v169 offset:128
	ds_read_b128 v[120:123], v169 offset:160
	ds_read_b128 v[128:131], v169 offset:6784
	ds_read_b128 v[176:179], v169 offset:6816
	s_waitcnt lgkmcnt(3)
	v_mfma_f32_32x32x16_bf16 v[48:63], v[136:139], v[88:91], v[48:63]
	v_mfma_f32_32x32x16_bf16 v[64:79], v[116:119], v[84:87], v[64:79]
	ds_read_b128 v[136:139], v170 offset:35840
	ds_read_b128 v[124:127], v170 offset:35872
	s_waitcnt lgkmcnt(3)
	v_mfma_f32_32x32x16_bf16 v[48:63], v[128:131], v[84:87], v[48:63]
	v_mfma_f32_32x32x16_bf16 v[64:79], v[120:123], v[80:83], v[64:79]
	ds_read_b128 v[132:135], v170 offset:35904
	ds_read_b128 v[120:123], v170 offset:35936
	ds_read_b128 v[144:147], v170 offset:40448
	ds_read_b128 v[140:143], v170 offset:40480
	ds_read_b128 v[128:131], v170 offset:40512
	ds_read_b128 v[116:119], v170 offset:40544
	s_waitcnt lgkmcnt(8)
	v_mfma_f32_32x32x16_bf16 v[48:63], v[176:179], v[80:83], v[48:63]
	s_add_i32 s43, s43, 1
	s_nop 3
	v_exp_f32_e32 v160, v64
	v_exp_f32_e32 v161, v65
	v_exp_f32_e32 v64, v66
	v_exp_f32_e32 v65, v67
	v_exp_f32_e32 v68, v68
	v_exp_f32_e32 v69, v69
	v_exp_f32_e32 v66, v70
	v_exp_f32_e32 v67, v71
	v_cvt_pk_bf16_f32 v176, v160, v161
	v_cvt_pk_bf16_f32 v177, v64, v65
	v_cvt_pk_bf16_f32 v178, v68, v69
	v_cvt_pk_bf16_f32 v179, v66, v67
	v_exp_f32_e32 v70, v74
	v_exp_f32_e32 v71, v75
	s_waitcnt lgkmcnt(0)
	v_mfma_f32_32x32x16_bf16 v[16:31], v[136:139], v[176:179], v[16:31]
	v_exp_f32_e32 v136, v72
	v_exp_f32_e32 v137, v73
	v_exp_f32_e32 v74, v76
	v_exp_f32_e32 v75, v77
	v_exp_f32_e32 v72, v78
	v_exp_f32_e32 v73, v79
	v_exp_f32_e32 v76, v48
	v_mfma_f32_32x32x16_bf16 v[0:15], v[144:147], v[176:179], v[0:15]
	v_cvt_pk_bf16_f32 v144, v136, v137
	v_cvt_pk_bf16_f32 v145, v70, v71
	v_cvt_pk_bf16_f32 v146, v74, v75
	v_cvt_pk_bf16_f32 v147, v72, v73
	v_exp_f32_e32 v77, v49
	v_exp_f32_e32 v48, v50
	v_exp_f32_e32 v49, v51
	v_mfma_f32_32x32x16_bf16 v[16:31], v[124:127], v[144:147], v[16:31]
	v_exp_f32_e32 v52, v52
	v_exp_f32_e32 v53, v53
	v_exp_f32_e32 v50, v54
	v_exp_f32_e32 v51, v55
	v_cvt_pk_bf16_f32 v124, v76, v77
	v_cvt_pk_bf16_f32 v125, v48, v49
	v_cvt_pk_bf16_f32 v126, v52, v53
	v_mfma_f32_32x32x16_bf16 v[0:15], v[140:143], v[144:147], v[0:15]
	v_cvt_pk_bf16_f32 v127, v50, v51
	v_exp_f32_e32 v78, v56
	v_exp_f32_e32 v79, v57
	v_exp_f32_e32 v54, v58
	v_exp_f32_e32 v55, v59
	v_exp_f32_e32 v58, v60
	v_exp_f32_e32 v59, v61
	v_mfma_f32_32x32x16_bf16 v[16:31], v[132:135], v[124:127], v[16:31]
	v_exp_f32_e32 v56, v62
	v_exp_f32_e32 v57, v63
	v_cvt_pk_bf16_f32 v60, v78, v79
	v_cvt_pk_bf16_f32 v61, v54, v55
	v_cvt_pk_bf16_f32 v62, v58, v59
	v_cvt_pk_bf16_f32 v63, v56, v57
	v_mfma_f32_32x32x16_bf16 v[0:15], v[128:131], v[124:127], v[0:15]
	v_mfma_f32_32x32x16_bf16 v[16:31], v[120:123], v[60:63], v[16:31]
	v_mfma_f32_32x32x16_bf16 v[0:15], v[116:119], v[60:63], v[0:15]
	s_waitcnt vmcnt(1)
	ds_write_b128 v244, v[104:107] offset:13312
	s_mov_b64 exec, s[8:9]
	ds_write_b128 v245, v[108:111] offset:13312
	s_mov_b64 exec, -1
	s_waitcnt vmcnt(0)
	ds_write2_b64 v247, v[112:113], v[114:115] offset1:2
	v_pk_add_f32 v[48:49], v[64:65], v[48:49]
	v_pk_add_f32 v[60:61], v[160:161], v[76:77]
	v_pk_add_f32 v[48:49], v[152:153], v[48:49]
	v_pk_add_f32 v[50:51], v[66:67], v[50:51]
	v_pk_add_f32 v[60:61], v[150:151], v[60:61]
	v_pk_add_f32 v[52:53], v[68:69], v[52:53]
	v_pk_add_f32 v[48:49], v[50:51], v[48:49]
	v_pk_add_f32 v[50:51], v[70:71], v[54:55]
	v_pk_add_f32 v[52:53], v[52:53], v[60:61]
	v_pk_add_f32 v[60:61], v[136:137], v[78:79]
	v_pk_add_f32 v[48:49], v[50:51], v[48:49]
	v_pk_add_f32 v[50:51], v[72:73], v[56:57]
	v_pk_add_f32 v[52:53], v[60:61], v[52:53]
	v_pk_add_f32 v[58:59], v[74:75], v[58:59]
	v_pk_add_f32 v[152:153], v[50:51], v[48:49]
	v_pk_add_f32 v[150:151], v[58:59], v[52:53]
	s_waitcnt lgkmcnt(0)
	s_barrier
	ds_read_b128 v[48:51], v169 offset:13312
	ds_read_b128 v[52:55], v169 offset:13344
	ds_read_b128 v[116:119], v169 offset:19968
	ds_read_b128 v[120:123], v169 offset:20000
	global_load_dwordx4 v[104:107], v154, s[98:99]
	s_mov_b64 exec, s[8:9]
	global_load_dwordx4 v[108:111], v156, s[98:99]
	s_mov_b64 exec, -1
	global_load_dwordx4 v[112:115], v158, s[100:101]
	s_add_u32 s98, s98, 0x18000
	s_addc_u32 s99, s99, 0
	s_add_u32 s100, s100, 0x80
	s_addc_u32 s101, s101, 0
	s_waitcnt lgkmcnt(3)
	v_mfma_f32_32x32x16_bf16 v[64:79], v[48:51], v[100:103], v[32:47]
	ds_read_b128 v[124:127], v169 offset:13376
	ds_read_b128 v[128:131], v169 offset:13408
	ds_read_b128 v[132:135], v169 offset:20032
	ds_read_b128 v[136:139], v169 offset:20064
	s_waitcnt lgkmcnt(4)
	v_mfma_f32_32x32x16_bf16 v[64:79], v[52:55], v[96:99], v[64:79]
	v_mfma_f32_32x32x16_bf16 v[48:63], v[116:119], v[100:103], v[32:47]
	v_mfma_f32_32x32x16_bf16 v[48:63], v[120:123], v[96:99], v[48:63]
	s_waitcnt lgkmcnt(1)
	v_mfma_f32_32x32x16_bf16 v[64:79], v[124:127], v[92:95], v[64:79]
	v_mfma_f32_32x32x16_bf16 v[48:63], v[132:135], v[92:95], v[48:63]
	v_mfma_f32_32x32x16_bf16 v[64:79], v[128:131], v[88:91], v[64:79]
	ds_read_b128 v[116:119], v169 offset:13440
	ds_read_b128 v[120:123], v169 offset:13472
	ds_read_b128 v[128:131], v169 offset:20096
	ds_read_b128 v[176:179], v169 offset:20128
	s_waitcnt lgkmcnt(3)
	v_mfma_f32_32x32x16_bf16 v[48:63], v[136:139], v[88:91], v[48:63]
	v_mfma_f32_32x32x16_bf16 v[64:79], v[116:119], v[84:87], v[64:79]
	ds_read_b128 v[136:139], v170 offset:45056
	ds_read_b128 v[124:127], v170 offset:45088
	s_waitcnt lgkmcnt(3)
	v_mfma_f32_32x32x16_bf16 v[48:63], v[128:131], v[84:87], v[48:63]
	v_mfma_f32_32x32x16_bf16 v[64:79], v[120:123], v[80:83], v[64:79]
	ds_read_b128 v[132:135], v170 offset:45120
	ds_read_b128 v[120:123], v170 offset:45152
	ds_read_b128 v[144:147], v170 offset:49664
	ds_read_b128 v[140:143], v170 offset:49696
	ds_read_b128 v[128:131], v170 offset:49728
	ds_read_b128 v[116:119], v170 offset:49760
	s_waitcnt lgkmcnt(8)
	v_mfma_f32_32x32x16_bf16 v[48:63], v[176:179], v[80:83], v[48:63]
	s_add_i32 s43, s43, 1
	s_nop 3
	v_exp_f32_e32 v160, v64
	v_exp_f32_e32 v161, v65
	v_exp_f32_e32 v64, v66
	v_exp_f32_e32 v65, v67
	v_exp_f32_e32 v68, v68
	v_exp_f32_e32 v69, v69
	v_exp_f32_e32 v66, v70
	v_exp_f32_e32 v67, v71
	v_cvt_pk_bf16_f32 v176, v160, v161
	v_cvt_pk_bf16_f32 v177, v64, v65
	v_cvt_pk_bf16_f32 v178, v68, v69
	v_cvt_pk_bf16_f32 v179, v66, v67
	v_exp_f32_e32 v70, v74
	v_exp_f32_e32 v71, v75
	s_waitcnt lgkmcnt(0)
	v_mfma_f32_32x32x16_bf16 v[16:31], v[136:139], v[176:179], v[16:31]
	v_exp_f32_e32 v136, v72
	v_exp_f32_e32 v137, v73
	v_exp_f32_e32 v74, v76
	v_exp_f32_e32 v75, v77
	v_exp_f32_e32 v72, v78
	v_exp_f32_e32 v73, v79
	v_exp_f32_e32 v76, v48
	v_mfma_f32_32x32x16_bf16 v[0:15], v[144:147], v[176:179], v[0:15]
	v_cvt_pk_bf16_f32 v144, v136, v137
	v_cvt_pk_bf16_f32 v145, v70, v71
	v_cvt_pk_bf16_f32 v146, v74, v75
	v_cvt_pk_bf16_f32 v147, v72, v73
	v_exp_f32_e32 v77, v49
	v_exp_f32_e32 v48, v50
	v_exp_f32_e32 v49, v51
	v_mfma_f32_32x32x16_bf16 v[16:31], v[124:127], v[144:147], v[16:31]
	v_exp_f32_e32 v52, v52
	v_exp_f32_e32 v53, v53
	v_exp_f32_e32 v50, v54
	v_exp_f32_e32 v51, v55
	v_cvt_pk_bf16_f32 v124, v76, v77
	v_cvt_pk_bf16_f32 v125, v48, v49
	v_cvt_pk_bf16_f32 v126, v52, v53
	v_mfma_f32_32x32x16_bf16 v[0:15], v[140:143], v[144:147], v[0:15]
	v_cvt_pk_bf16_f32 v127, v50, v51
	v_exp_f32_e32 v78, v56
	v_exp_f32_e32 v79, v57
	v_exp_f32_e32 v54, v58
	v_exp_f32_e32 v55, v59
	v_exp_f32_e32 v58, v60
	v_exp_f32_e32 v59, v61
	v_mfma_f32_32x32x16_bf16 v[16:31], v[132:135], v[124:127], v[16:31]
	v_exp_f32_e32 v56, v62
	v_exp_f32_e32 v57, v63
	v_cvt_pk_bf16_f32 v60, v78, v79
	v_cvt_pk_bf16_f32 v61, v54, v55
	v_cvt_pk_bf16_f32 v62, v58, v59
	v_cvt_pk_bf16_f32 v63, v56, v57
	v_mfma_f32_32x32x16_bf16 v[0:15], v[128:131], v[124:127], v[0:15]
	v_mfma_f32_32x32x16_bf16 v[16:31], v[120:123], v[60:63], v[16:31]
	v_mfma_f32_32x32x16_bf16 v[0:15], v[116:119], v[60:63], v[0:15]
	s_waitcnt vmcnt(1)
	ds_write_b128 v244, v[104:107]
	s_mov_b64 exec, s[8:9]
	ds_write_b128 v245, v[108:111]
	s_mov_b64 exec, -1
	s_waitcnt vmcnt(0)
	ds_write2_b64 v243, v[112:113], v[114:115] offset1:2
	v_pk_add_f32 v[48:49], v[64:65], v[48:49]
	v_pk_add_f32 v[60:61], v[160:161], v[76:77]
	v_pk_add_f32 v[48:49], v[152:153], v[48:49]
	v_pk_add_f32 v[50:51], v[66:67], v[50:51]
	v_pk_add_f32 v[60:61], v[150:151], v[60:61]
	v_pk_add_f32 v[52:53], v[68:69], v[52:53]
	v_pk_add_f32 v[48:49], v[50:51], v[48:49]
	v_pk_add_f32 v[50:51], v[70:71], v[54:55]
	v_pk_add_f32 v[52:53], v[52:53], v[60:61]
	v_pk_add_f32 v[60:61], v[136:137], v[78:79]
	v_pk_add_f32 v[48:49], v[50:51], v[48:49]
	v_pk_add_f32 v[50:51], v[72:73], v[56:57]
	v_pk_add_f32 v[52:53], v[60:61], v[52:53]
	v_pk_add_f32 v[58:59], v[74:75], v[58:59]
	v_pk_add_f32 v[152:153], v[50:51], v[48:49]
	v_pk_add_f32 v[150:151], v[58:59], v[52:53]
	s_waitcnt lgkmcnt(0)
	s_barrier
	ds_read_b128 v[48:51], v169
	ds_read_b128 v[52:55], v169 offset:32
	ds_read_b128 v[116:119], v169 offset:6656
	ds_read_b128 v[120:123], v169 offset:6688
	global_load_dwordx4 v[104:107], v154, s[98:99]
	s_mov_b64 exec, s[8:9]
	global_load_dwordx4 v[108:111], v156, s[98:99]
	s_mov_b64 exec, -1
	global_load_dwordx4 v[112:115], v158, s[100:101]
	s_add_u32 s98, s98, 0x18000
	s_addc_u32 s99, s99, 0
	s_add_u32 s100, s100, 0x80
	s_addc_u32 s101, s101, 0
	s_waitcnt lgkmcnt(3)
	v_mfma_f32_32x32x16_bf16 v[64:79], v[48:51], v[100:103], v[32:47]
	ds_read_b128 v[124:127], v169 offset:64
	ds_read_b128 v[128:131], v169 offset:96
	ds_read_b128 v[132:135], v169 offset:6720
	ds_read_b128 v[136:139], v169 offset:6752
	s_waitcnt lgkmcnt(4)
	v_mfma_f32_32x32x16_bf16 v[64:79], v[52:55], v[96:99], v[64:79]
	v_mfma_f32_32x32x16_bf16 v[48:63], v[116:119], v[100:103], v[32:47]
	v_mfma_f32_32x32x16_bf16 v[48:63], v[120:123], v[96:99], v[48:63]
	s_waitcnt lgkmcnt(1)
	v_mfma_f32_32x32x16_bf16 v[64:79], v[124:127], v[92:95], v[64:79]
	v_mfma_f32_32x32x16_bf16 v[48:63], v[132:135], v[92:95], v[48:63]
	v_mfma_f32_32x32x16_bf16 v[64:79], v[128:131], v[88:91], v[64:79]
	ds_read_b128 v[116:119], v169 offset:128
	ds_read_b128 v[120:123], v169 offset:160
	ds_read_b128 v[128:131], v169 offset:6784
	ds_read_b128 v[176:179], v169 offset:6816
	s_waitcnt lgkmcnt(3)
	v_mfma_f32_32x32x16_bf16 v[48:63], v[136:139], v[88:91], v[48:63]
	v_mfma_f32_32x32x16_bf16 v[64:79], v[116:119], v[84:87], v[64:79]
	ds_read_b128 v[136:139], v170 offset:26624
	ds_read_b128 v[124:127], v170 offset:26656
	s_waitcnt lgkmcnt(3)
	v_mfma_f32_32x32x16_bf16 v[48:63], v[128:131], v[84:87], v[48:63]
	v_mfma_f32_32x32x16_bf16 v[64:79], v[120:123], v[80:83], v[64:79]
	ds_read_b128 v[132:135], v170 offset:26688
	ds_read_b128 v[120:123], v170 offset:26720
	ds_read_b128 v[144:147], v170 offset:31232
	ds_read_b128 v[140:143], v170 offset:31264
	ds_read_b128 v[128:131], v170 offset:31296
	ds_read_b128 v[116:119], v170 offset:31328
	s_waitcnt lgkmcnt(8)
	v_mfma_f32_32x32x16_bf16 v[48:63], v[176:179], v[80:83], v[48:63]
	s_add_i32 s43, s43, 1
	s_nop 3
	v_exp_f32_e32 v160, v64
	v_exp_f32_e32 v161, v65
	v_exp_f32_e32 v64, v66
	v_exp_f32_e32 v65, v67
	v_exp_f32_e32 v68, v68
	v_exp_f32_e32 v69, v69
	v_exp_f32_e32 v66, v70
	v_exp_f32_e32 v67, v71
	v_cvt_pk_bf16_f32 v176, v160, v161
	v_cvt_pk_bf16_f32 v177, v64, v65
	v_cvt_pk_bf16_f32 v178, v68, v69
	v_cvt_pk_bf16_f32 v179, v66, v67
	v_exp_f32_e32 v70, v74
	v_exp_f32_e32 v71, v75
	s_waitcnt lgkmcnt(0)
	v_mfma_f32_32x32x16_bf16 v[16:31], v[136:139], v[176:179], v[16:31]
	v_exp_f32_e32 v136, v72
	v_exp_f32_e32 v137, v73
	v_exp_f32_e32 v74, v76
	v_exp_f32_e32 v75, v77
	v_exp_f32_e32 v72, v78
	v_exp_f32_e32 v73, v79
	v_exp_f32_e32 v76, v48
	v_mfma_f32_32x32x16_bf16 v[0:15], v[144:147], v[176:179], v[0:15]
	v_cvt_pk_bf16_f32 v144, v136, v137
	v_cvt_pk_bf16_f32 v145, v70, v71
	v_cvt_pk_bf16_f32 v146, v74, v75
	v_cvt_pk_bf16_f32 v147, v72, v73
	v_exp_f32_e32 v77, v49
	v_exp_f32_e32 v48, v50
	v_exp_f32_e32 v49, v51
	v_mfma_f32_32x32x16_bf16 v[16:31], v[124:127], v[144:147], v[16:31]
	v_exp_f32_e32 v52, v52
	v_exp_f32_e32 v53, v53
	v_exp_f32_e32 v50, v54
	v_exp_f32_e32 v51, v55
	v_cvt_pk_bf16_f32 v124, v76, v77
	v_cvt_pk_bf16_f32 v125, v48, v49
	v_cvt_pk_bf16_f32 v126, v52, v53
	v_mfma_f32_32x32x16_bf16 v[0:15], v[140:143], v[144:147], v[0:15]
	v_cvt_pk_bf16_f32 v127, v50, v51
	v_exp_f32_e32 v78, v56
	v_exp_f32_e32 v79, v57
	v_exp_f32_e32 v54, v58
	v_exp_f32_e32 v55, v59
	v_exp_f32_e32 v58, v60
	v_exp_f32_e32 v59, v61
	v_mfma_f32_32x32x16_bf16 v[16:31], v[132:135], v[124:127], v[16:31]
	v_exp_f32_e32 v56, v62
	v_exp_f32_e32 v57, v63
	v_cvt_pk_bf16_f32 v60, v78, v79
	v_cvt_pk_bf16_f32 v61, v54, v55
	v_cvt_pk_bf16_f32 v62, v58, v59
	v_cvt_pk_bf16_f32 v63, v56, v57
	v_mfma_f32_32x32x16_bf16 v[0:15], v[128:131], v[124:127], v[0:15]
	v_mfma_f32_32x32x16_bf16 v[16:31], v[120:123], v[60:63], v[16:31]
	v_mfma_f32_32x32x16_bf16 v[0:15], v[116:119], v[60:63], v[0:15]
	s_waitcnt vmcnt(1)
	ds_write_b128 v244, v[104:107] offset:13312
	s_mov_b64 exec, s[8:9]
	ds_write_b128 v245, v[108:111] offset:13312
	s_mov_b64 exec, -1
	s_waitcnt vmcnt(0)
	ds_write2_b64 v246, v[112:113], v[114:115] offset1:2
	v_pk_add_f32 v[48:49], v[64:65], v[48:49]
	v_pk_add_f32 v[60:61], v[160:161], v[76:77]
	v_pk_add_f32 v[48:49], v[152:153], v[48:49]
	v_pk_add_f32 v[50:51], v[66:67], v[50:51]
	v_pk_add_f32 v[60:61], v[150:151], v[60:61]
	v_pk_add_f32 v[52:53], v[68:69], v[52:53]
	v_pk_add_f32 v[48:49], v[50:51], v[48:49]
	v_pk_add_f32 v[50:51], v[70:71], v[54:55]
	v_pk_add_f32 v[52:53], v[52:53], v[60:61]
	v_pk_add_f32 v[60:61], v[136:137], v[78:79]
	v_pk_add_f32 v[48:49], v[50:51], v[48:49]
	v_pk_add_f32 v[50:51], v[72:73], v[56:57]
	v_pk_add_f32 v[52:53], v[60:61], v[52:53]
	v_pk_add_f32 v[58:59], v[74:75], v[58:59]
	v_pk_add_f32 v[152:153], v[50:51], v[48:49]
	v_pk_add_f32 v[150:151], v[58:59], v[52:53]
	s_waitcnt lgkmcnt(0)
	s_barrier
	s_branch .Lmla_loop
.Lmla_renorm:
	v_mov_b32_e32 v160, v148
	s_nop 1
	v_permlane32_swap_b32_e32 v148, v160
	v_max_f32_e32 v148, v148, v160
	v_cmp_nge_f32_e32 vcc, 0x53800000, v148
	s_cbranch_vccz .Lmla_renorm_ok
	s_mov_b32 s64, 1
.Lmla_renorm_ok:
	v_frexp_exp_i32_f32_e32 v160, v148
	v_max_i32_e32 v160, 0, v160
	v_cvt_f32_i32_e32 v161, v160
	v_sub_u32_e32 v160, 0, v160
	v_ldexp_f32 v160, 1.0, v160
	v_add_f32_e32 v168, v168, v161
	v_xor_b32_e32 v32, 0x80000000, v168
	v_mov_b32_e32 v33, v32
	v_mov_b32_e32 v34, v32
	v_mov_b32_e32 v35, v32
	v_mov_b32_e32 v36, v32
	v_mov_b32_e32 v37, v32
	v_mov_b32_e32 v38, v32
	v_mov_b32_e32 v39, v32
	v_mov_b32_e32 v40, v32
	v_mov_b32_e32 v41, v32
	v_mov_b32_e32 v42, v32
	v_mov_b32_e32 v43, v32
	v_mov_b32_e32 v44, v32
	v_mov_b32_e32 v45, v32
	v_mov_b32_e32 v46, v32
	v_mov_b32_e32 v47, v32
	v_pk_mul_f32 v[0:1], v[0:1], v[160:161] op_sel_hi:[1,0]
	v_pk_mul_f32 v[2:3], v[2:3], v[160:161] op_sel_hi:[1,0]
	v_pk_mul_f32 v[4:5], v[4:5], v[160:161] op_sel_hi:[1,0]
	v_pk_mul_f32 v[6:7], v[6:7], v[160:161] op_sel_hi:[1,0]
	v_pk_mul_f32 v[8:9], v[8:9], v[160:161] op_sel_hi:[1,0]
	v_pk_mul_f32 v[10:11], v[10:11], v[160:161] op_sel_hi:[1,0]
	v_pk_mul_f32 v[12:13], v[12:13], v[160:161] op_sel_hi:[1,0]
	v_pk_mul_f32 v[14:15], v[14:15], v[160:161] op_sel_hi:[1,0]
	v_pk_mul_f32 v[16:17], v[16:17], v[160:161] op_sel_hi:[1,0]
	v_pk_mul_f32 v[18:19], v[18:19], v[160:161] op_sel_hi:[1,0]
	v_pk_mul_f32 v[20:21], v[20:21], v[160:161] op_sel_hi:[1,0]
	v_pk_mul_f32 v[22:23], v[22:23], v[160:161] op_sel_hi:[1,0]
	v_pk_mul_f32 v[24:25], v[24:25], v[160:161] op_sel_hi:[1,0]
	v_pk_mul_f32 v[26:27], v[26:27], v[160:161] op_sel_hi:[1,0]
	v_pk_mul_f32 v[28:29], v[28:29], v[160:161] op_sel_hi:[1,0]
	v_pk_mul_f32 v[30:31], v[30:31], v[160:161] op_sel_hi:[1,0]
	v_pk_mul_f32 v[150:151], v[150:151], v[160:161] op_sel_hi:[1,0]
	v_pk_mul_f32 v[152:153], v[152:153], v[160:161] op_sel_hi:[1,0]
	s_branch .Lmla_renorm_back

; #define AT_QK_LD0(kb_) do { if constexpr (NEGM) { const LAS unsigned char* kbp_ = Kl + (kb_) * KBUF + r32 * KROWB + hi * 16; AT_KLD2(0); __builtin_amdgcn_sched_barrier(0); } } while (0)
; template <int DQK, int DV, int RH, bool NEGM> ...
;     ...
;         for (int t = 0; t < NT; ++t) {
;             const int kb = t & 1;
;             if (t + 1 < NT) AT_GLOAD(t + 1);
;             f32x16 p[RH][2];
;             AT_QK_LD0(kb); AT_QK(kb); AT_VLOAD(vs_cur); AT_SOFTMAX(); AT_PV(vs_cur);
;             if (t + 1 < NT) AT_LSTORE(kb ^ 1, vs_next);
;             __syncthreads();
;             vs_prev = vs_cur; vs_cur = vs_next; vs_next = (vs_next == 2) ? 0 : vs_next + 1;
.Lmla_redo:
	s_barrier
	v_mov_b32_e32 v241, 0x10000
	ds_write_b32 v241, v149
	s_waitcnt lgkmcnt(0)
	s_mov_b32 s64, 0
	s_mov_b32 s65, 1
	s_branch .LBB0_863
.Lmla_exit:
	s_mov_b32 s21, 0
	v_max3_f32 v148, v150, v151, v152
	v_max_f32_e32 v148, v148, v153
	v_cmp_nge_f32_e32 vcc, 0x53800000, v148
	s_cbranch_vccz .Lmla_exit_ok
	s_mov_b32 s64, 1
.Lmla_exit_ok:
	s_andn2_b32 s64, s64, s65
	s_cmp_eq_u32 s64, 0
	s_cbranch_scc1 .Lmla_exit_nf
	v_mov_b32_e32 v148, 1
	v_mov_b32_e32 v160, 0x10000
	ds_write_b32 v160, v148
.Lmla_exit_nf:
	ds_read_b128 v[64:67], v169 offset:13312
	ds_read_b128 v[68:71], v169 offset:13344
	ds_read_b128 v[72:75], v169 offset:19968
	ds_read_b128 v[76:79], v169 offset:20000
	s_waitcnt lgkmcnt(3)
	v_mfma_f32_32x32x16_bf16 v[48:63], v[64:67], v[100:103], v[32:47]
	ds_read_b128 v[64:67], v169 offset:13376
	ds_read_b128 v[104:107], v169 offset:13408
	ds_read_b128 v[108:111], v169 offset:20032
	ds_read_b128 v[112:115], v169 offset:20064
	s_waitcnt lgkmcnt(6)
	v_mfma_f32_32x32x16_bf16 v[48:63], v[68:71], v[96:99], v[48:63]
	s_waitcnt lgkmcnt(5)
	v_mfma_f32_32x32x16_bf16 v[32:47], v[72:75], v[100:103], v[32:47]
	s_waitcnt lgkmcnt(4)
	v_mfma_f32_32x32x16_bf16 v[32:47], v[76:79], v[96:99], v[32:47]
	s_waitcnt lgkmcnt(3)
	v_mfma_f32_32x32x16_bf16 v[48:63], v[64:67], v[92:95], v[48:63]
	ds_read_b128 v[64:67], v169 offset:13440
	ds_read_b128 v[68:71], v169 offset:13472
	ds_read_b128 v[72:75], v169 offset:20096
	ds_read_b128 v[76:79], v169 offset:20128
	s_waitcnt lgkmcnt(5)
	v_mfma_f32_32x32x16_bf16 v[32:47], v[108:111], v[92:95], v[32:47]
	v_mfma_f32_32x32x16_bf16 v[48:63], v[104:107], v[88:91], v[48:63]
	s_waitcnt lgkmcnt(4)
	v_mfma_f32_32x32x16_bf16 v[32:47], v[112:115], v[88:91], v[32:47]
	s_waitcnt lgkmcnt(3)
	v_mfma_f32_32x32x16_bf16 v[48:63], v[64:67], v[84:87], v[48:63]
	v_add3_u32 v64, v167, s21, v173
	v_add_u32_e32 v65, 0x6800, v64
	ds_read_b128 v[108:111], v65
	ds_read_b128 v[104:107], v65 offset:32
	ds_read_b128 v[96:99], v65 offset:64
	ds_read_b128 v[88:91], v65 offset:96
	s_waitcnt lgkmcnt(5)
	v_mfma_f32_32x32x16_bf16 v[32:47], v[72:75], v[84:87], v[32:47]
	ds_read_b128 v[112:115], v65 offset:4608
	ds_read_b128 v[100:103], v65 offset:4640
	ds_read_b128 v[92:95], v65 offset:4672
	ds_read_b128 v[84:87], v65 offset:4704
	v_mfma_f32_32x32x16_bf16 v[48:63], v[68:71], v[80:83], v[48:63]
	s_waitcnt lgkmcnt(8)
	v_mfma_f32_32x32x16_bf16 v[32:47], v[76:79], v[80:83], v[32:47]
	s_nop 11
	v_max_f32_e32 v64, v32, v32
	v_max_f32_e32 v65, v48, v48
	v_max_f32_e32 v64, v65, v64
	v_max_f32_e32 v65, v33, v33
	v_max_f32_e32 v66, v49, v49
	v_max_f32_e32 v65, v66, v65
	v_max_f32_e32 v66, v35, v35
	v_max_f32_e32 v67, v51, v51
	v_max_f32_e32 v66, v67, v66
	v_max3_f32 v67, v50, v34, v54
	v_max3_f32 v66, v66, v55, v39
	v_max3_f32 v64, v64, v52, v36
	v_max3_f32 v65, v65, v53, v37
	v_max3_f32 v67, v67, v38, v58
	v_max3_f32 v66, v66, v59, v43
	v_max3_f32 v64, v64, v56, v40
	v_max3_f32 v65, v65, v57, v41
	v_max3_f32 v67, v67, v42, v62
	v_max3_f32 v66, v66, v63, v47
	v_max3_f32 v64, v64, v60, v44
	v_max3_f32 v65, v65, v61, v45
	v_max3_f32 v66, v67, v46, v66
	v_max3_f32 v64, v64, v65, v66
	v_mov_b32_e32 v65, v64
	s_nop 1
	v_permlane32_swap_b32_e32 v64, v65
	v_max_f32_e32 v65, v65, v65
	v_max_f32_e32 v64, v64, v64
	v_max_f32_e32 v64, v64, v65
	v_cmp_lt_f32_e32 vcc, s59, v64
	s_cbranch_vccnz .LBB0_861
	v_mov_b32_e32 v64, v151
	v_mov_b32_e32 v151, v152
	v_mov_b32_e32 v65, v153
	s_branch .LBB0_862
